# scan: global-load ISSUE moved out of stage Y (waves 0-3 issue in next stage X, waves 4-7 at start of next stage S), exact vmcnt in COMMIT
# speedup vs baseline: 1.0053x; 1.0053x over previous
.Lsx0_a:
	v_add_u32_e32 v192, v144, v145
	v_add_u32_e32 v199, v150, v145
	s_and_saveexec_b64 s[2:3], s[54:55]
	s_cbranch_execz .Lsx0_c
	s_cmp_eq_u32 s36, 0
	s_cbranch_scc1 .Lis0a
	s_cmp_gt_u32 s36, 62
	s_cbranch_scc1 .Lis0a
	s_add_i32 s24, s19, 0xffffffc0
	s_add_i32 s25, s21, 0x30
	s_and_b64 s[98:99], s[12:13], exec
	s_cselect_b32 s24, s25, s24
	v_lshl_add_u32 v194, s24, 6, v183
	v_lshlrev_b64 v[112:113], 1, v[194:195]
	v_lshl_add_u64 v[114:115], s[44:45], 0, v[112:113]
	global_load_dword v5, v[114:115], off
	v_lshl_add_u64 v[114:115], s[42:43], 0, v[112:113]
	global_load_dword v6, v[114:115], off
	v_lshl_add_u64 v[114:115], s[0:1], 0, v[112:113]
	global_load_dword v7, v[114:115], off
	v_lshl_add_u64 v[114:115], s[34:35], 0, v[112:113]
	global_load_dword v8, v[114:115], off
	v_lshl_add_u64 v[114:115], s[76:77], 0, v[112:113]
	global_load_dword v9, v[114:115], off
	v_add_u32_e32 v194, s24, v184
	v_lshl_add_u64 v[114:115], v[194:195], 2, s[40:41]
	global_load_dword v110, v[114:115], off
.Lis0a:
	s_cmp_lg_u32 s21, 0
	s_cbranch_scc0 .Lsx0_c
	s_waitcnt lgkmcnt(0)
	v_cvt_pk_bf16_f32 v240, v236, v237
	global_store_dword v[238:239], v240, off

.LBB0_403:
	s_or_b64 exec, exec, s[2:3]
	s_waitcnt lgkmcnt(0)
	s_barrier
	v_add_u32_e32 v191, 0x17d00, v177
	s_and_saveexec_b64 s[2:3], s[56:57]
	s_cbranch_execz .Lis0c
	s_cmp_eq_u32 s36, 0
	s_cbranch_scc1 .Lis0b
	s_cmp_gt_u32 s36, 62
	s_cbranch_scc1 .Lis0b
	s_add_i32 s24, s19, 0xffffffc0
	s_add_i32 s25, s21, 0x30
	s_and_b64 s[98:99], s[12:13], exec
	s_cselect_b32 s24, s25, s24
	v_lshl_add_u32 v194, s24, 6, v183
	v_lshlrev_b64 v[112:113], 1, v[194:195]
	v_lshl_add_u64 v[114:115], s[44:45], 0, v[112:113]
	global_load_dword v5, v[114:115], off
	v_lshl_add_u64 v[114:115], s[42:43], 0, v[112:113]
	global_load_dword v6, v[114:115], off
	v_lshl_add_u64 v[114:115], s[0:1], 0, v[112:113]
	global_load_dword v7, v[114:115], off
	v_lshl_add_u64 v[114:115], s[34:35], 0, v[112:113]
	global_load_dword v8, v[114:115], off
	v_lshl_add_u64 v[114:115], s[76:77], 0, v[112:113]
	global_load_dword v9, v[114:115], off
	v_add_u32_e32 v194, s24, v184
	v_lshl_add_u64 v[114:115], v[194:195], 2, s[40:41]
	global_load_dword v110, v[114:115], off
.Lis0b:
.Lis0c:
	s_or_b64 exec, exec, s[2:3]
	s_and_saveexec_b64 s[2:3], s[48:49]
	s_cbranch_execz .LBB0_405
	s_setprio 3
	v_mov_b32_e32 v23, 0x17900
	ds_read2st64_b32 v[32:33], v191 offset0:0 offset1:1
	ds_read_b128 v[48:51], v23 offset:0
	ds_read2st64_b32 v[34:35], v191 offset0:2 offset1:3
	ds_read2st64_b32 v[36:37], v191 offset0:4 offset1:5
	ds_read_b128 v[52:55], v23 offset:16
	ds_read2st64_b32 v[38:39], v191 offset0:6 offset1:7
	ds_read2st64_b32 v[40:41], v191 offset0:8 offset1:9
	ds_read_b128 v[56:59], v23 offset:32
	ds_read2st64_b32 v[42:43], v191 offset0:10 offset1:11
	ds_read2st64_b32 v[44:45], v191 offset0:12 offset1:13
	ds_read_b128 v[60:63], v23 offset:48
	ds_read2st64_b32 v[46:47], v191 offset0:14 offset1:15
	ds_read_b128 v[64:67], v23 offset:64
	ds_read_b128 v[68:71], v23 offset:80
	ds_read_b128 v[72:75], v23 offset:96
	s_waitcnt lgkmcnt(13)
	v_fmac_f32_e32 v33, v49, v32
	s_waitcnt lgkmcnt(12)
	v_pk_fma_f32 v[34:35], v[50:51], v[32:33], v[34:35] op_sel_hi:[1,0,1]
	ds_read_b128 v[76:79], v23 offset:112
	s_waitcnt lgkmcnt(11)
	v_pk_fma_f32 v[36:37], v[52:53], v[32:33], v[36:37] op_sel_hi:[1,0,1]
	ds_read_b128 v[80:83], v23 offset:128
	ds_read_b128 v[84:87], v23 offset:144
	s_waitcnt lgkmcnt(12)
	v_pk_fma_f32 v[38:39], v[54:55], v[32:33], v[38:39] op_sel_hi:[1,0,1]
	ds_read_b128 v[88:91], v23 offset:160
	s_waitcnt lgkmcnt(11)
	v_pk_fma_f32 v[40:41], v[56:57], v[32:33], v[40:41] op_sel_hi:[1,0,1]
	ds_read_b128 v[92:95], v23 offset:176
	ds_read_b128 v[112:115], v23 offset:208
	s_waitcnt lgkmcnt(12)
	v_pk_fma_f32 v[42:43], v[58:59], v[32:33], v[42:43] op_sel_hi:[1,0,1]
	ds_read_b128 v[116:119], v23 offset:224
	s_waitcnt lgkmcnt(11)
	v_pk_fma_f32 v[44:45], v[60:61], v[32:33], v[44:45] op_sel_hi:[1,0,1]
	ds_read_b128 v[120:123], v23 offset:240
	ds_read_b128 v[124:127], v23 offset:272
	s_waitcnt lgkmcnt(12)
	v_pk_fma_f32 v[46:47], v[62:63], v[32:33], v[46:47] op_sel_hi:[1,0,1]
	ds_read_b128 v[128:131], v23 offset:288
	s_waitcnt lgkmcnt(12)
	v_pk_fma_f32 v[34:35], v[66:67], v[32:33], v[34:35] op_sel:[0,1,0] op_sel_hi:[1,1,1]
	ds_read_b128 v[132:135], v23 offset:304
	s_waitcnt lgkmcnt(12)
	v_pk_fma_f32 v[36:37], v[68:69], v[32:33], v[36:37] op_sel:[0,1,0] op_sel_hi:[1,1,1]
	ds_read_b128 v[204:207], v23 offset:336
	v_pk_fma_f32 v[38:39], v[70:71], v[32:33], v[38:39] op_sel:[0,1,0] op_sel_hi:[1,1,1]
	s_waitcnt lgkmcnt(12)
	v_pk_fma_f32 v[40:41], v[72:73], v[32:33], v[40:41] op_sel:[0,1,0] op_sel_hi:[1,1,1]
	ds_read_b128 v[208:211], v23 offset:352
	v_pk_fma_f32 v[42:43], v[74:75], v[32:33], v[42:43] op_sel:[0,1,0] op_sel_hi:[1,1,1]
	s_waitcnt lgkmcnt(12)
	v_pk_fma_f32 v[44:45], v[76:77], v[32:33], v[44:45] op_sel:[0,1,0] op_sel_hi:[1,1,1]
	ds_read_b128 v[212:215], v23 offset:368
	v_pk_fma_f32 v[46:47], v[78:79], v[32:33], v[46:47] op_sel:[0,1,0] op_sel_hi:[1,1,1]
	s_waitcnt lgkmcnt(12)
	v_fmac_f32_e32 v35, v83, v34
	ds_read_b128 v[216:219], v23 offset:400
	s_waitcnt lgkmcnt(12)
	v_pk_fma_f32 v[36:37], v[84:85], v[34:35], v[36:37] op_sel_hi:[1,0,1]
	ds_read_b128 v[228:231], v23 offset:416
	v_pk_fma_f32 v[38:39], v[86:87], v[34:35], v[38:39] op_sel_hi:[1,0,1]
	s_waitcnt lgkmcnt(12)
	v_pk_fma_f32 v[40:41], v[88:89], v[34:35], v[40:41] op_sel_hi:[1,0,1]
	ds_read_b128 v[232:235], v23 offset:432
	v_pk_fma_f32 v[42:43], v[90:91], v[34:35], v[42:43] op_sel_hi:[1,0,1]
	s_waitcnt lgkmcnt(12)
	v_pk_fma_f32 v[44:45], v[92:93], v[34:35], v[44:45] op_sel_hi:[1,0,1]
	ds_read_b128 v[48:51], v23 offset:480
	v_pk_fma_f32 v[46:47], v[94:95], v[34:35], v[46:47] op_sel_hi:[1,0,1]
	s_waitcnt lgkmcnt(12)
	v_pk_fma_f32 v[36:37], v[112:113], v[34:35], v[36:37] op_sel:[0,1,0] op_sel_hi:[1,1,1]
	ds_read_b128 v[52:55], v23 offset:496
	v_pk_fma_f32 v[38:39], v[114:115], v[34:35], v[38:39] op_sel:[0,1,0] op_sel_hi:[1,1,1]
	s_waitcnt lgkmcnt(12)
	v_pk_fma_f32 v[40:41], v[116:117], v[34:35], v[40:41] op_sel:[0,1,0] op_sel_hi:[1,1,1]
	ds_read_b128 v[56:59], v23 offset:544
	v_pk_fma_f32 v[42:43], v[118:119], v[34:35], v[42:43] op_sel:[0,1,0] op_sel_hi:[1,1,1]
	s_waitcnt lgkmcnt(12)
	v_pk_fma_f32 v[44:45], v[120:121], v[34:35], v[44:45] op_sel:[0,1,0] op_sel_hi:[1,1,1]
	ds_read_b128 v[60:63], v23 offset:560
	v_pk_fma_f32 v[46:47], v[122:123], v[34:35], v[46:47] op_sel:[0,1,0] op_sel_hi:[1,1,1]
	s_waitcnt lgkmcnt(12)
	v_fmac_f32_e32 v37, v125, v36
	ds_read_b128 v[64:67], v23 offset:608
	v_pk_fma_f32 v[38:39], v[126:127], v[36:37], v[38:39] op_sel_hi:[1,0,1]
	s_waitcnt lgkmcnt(12)
	v_pk_fma_f32 v[40:41], v[128:129], v[36:37], v[40:41] op_sel_hi:[1,0,1]
	ds_read_b128 v[68:71], v23 offset:624
	v_pk_fma_f32 v[42:43], v[130:131], v[36:37], v[42:43] op_sel_hi:[1,0,1]
	s_waitcnt lgkmcnt(12)
	v_pk_fma_f32 v[44:45], v[132:133], v[36:37], v[44:45] op_sel_hi:[1,0,1]
	ds_read_b128 v[72:75], v23 offset:672
	v_pk_fma_f32 v[46:47], v[134:135], v[36:37], v[46:47] op_sel_hi:[1,0,1]
	s_waitcnt lgkmcnt(12)
	v_pk_fma_f32 v[38:39], v[206:207], v[36:37], v[38:39] op_sel:[0,1,0] op_sel_hi:[1,1,1]
	ds_read_b128 v[76:79], v23 offset:688
	s_waitcnt lgkmcnt(12)
	v_pk_fma_f32 v[40:41], v[208:209], v[36:37], v[40:41] op_sel:[0,1,0] op_sel_hi:[1,1,1]
	ds_read_b128 v[80:83], v23 offset:752
	v_pk_fma_f32 v[42:43], v[210:211], v[36:37], v[42:43] op_sel:[0,1,0] op_sel_hi:[1,1,1]
	s_waitcnt lgkmcnt(12)
	v_pk_fma_f32 v[44:45], v[212:213], v[36:37], v[44:45] op_sel:[0,1,0] op_sel_hi:[1,1,1]
	ds_read_b128 v[84:87], v23 offset:816
	v_pk_fma_f32 v[46:47], v[214:215], v[36:37], v[46:47] op_sel:[0,1,0] op_sel_hi:[1,1,1]
	s_waitcnt lgkmcnt(12)
	v_fmac_f32_e32 v39, v219, v38
	ds_read_b128 v[88:91], v23 offset:880
	s_waitcnt lgkmcnt(12)
	v_pk_fma_f32 v[40:41], v[228:229], v[38:39], v[40:41] op_sel_hi:[1,0,1]
	ds_read_b128 v[92:95], v23 offset:944
	v_pk_fma_f32 v[42:43], v[230:231], v[38:39], v[42:43] op_sel_hi:[1,0,1]
	s_waitcnt lgkmcnt(12)
	v_pk_fma_f32 v[44:45], v[232:233], v[38:39], v[44:45] op_sel_hi:[1,0,1]
	v_pk_fma_f32 v[46:47], v[234:235], v[38:39], v[46:47] op_sel_hi:[1,0,1]
	s_waitcnt lgkmcnt(11)
	v_pk_fma_f32 v[40:41], v[48:49], v[38:39], v[40:41] op_sel:[0,1,0] op_sel_hi:[1,1,1]
	v_pk_fma_f32 v[42:43], v[50:51], v[38:39], v[42:43] op_sel:[0,1,0] op_sel_hi:[1,1,1]
	s_waitcnt lgkmcnt(10)
	v_pk_fma_f32 v[44:45], v[52:53], v[38:39], v[44:45] op_sel:[0,1,0] op_sel_hi:[1,1,1]
	v_pk_fma_f32 v[46:47], v[54:55], v[38:39], v[46:47] op_sel:[0,1,0] op_sel_hi:[1,1,1]
	s_waitcnt lgkmcnt(9)
	v_fmac_f32_e32 v41, v57, v40
	v_pk_fma_f32 v[42:43], v[58:59], v[40:41], v[42:43] op_sel_hi:[1,0,1]
	s_waitcnt lgkmcnt(8)
	v_pk_fma_f32 v[44:45], v[60:61], v[40:41], v[44:45] op_sel_hi:[1,0,1]
	v_pk_fma_f32 v[46:47], v[62:63], v[40:41], v[46:47] op_sel_hi:[1,0,1]
	s_waitcnt lgkmcnt(7)
	v_pk_fma_f32 v[42:43], v[66:67], v[40:41], v[42:43] op_sel:[0,1,0] op_sel_hi:[1,1,1]
	s_waitcnt lgkmcnt(6)
	v_pk_fma_f32 v[44:45], v[68:69], v[40:41], v[44:45] op_sel:[0,1,0] op_sel_hi:[1,1,1]
	v_pk_fma_f32 v[46:47], v[70:71], v[40:41], v[46:47] op_sel:[0,1,0] op_sel_hi:[1,1,1]
	s_waitcnt lgkmcnt(5)
	v_fmac_f32_e32 v43, v75, v42
	s_waitcnt lgkmcnt(4)
	v_pk_fma_f32 v[44:45], v[76:77], v[42:43], v[44:45] op_sel_hi:[1,0,1]
	v_pk_fma_f32 v[46:47], v[78:79], v[42:43], v[46:47] op_sel_hi:[1,0,1]
	s_waitcnt lgkmcnt(3)
	v_pk_fma_f32 v[44:45], v[80:81], v[42:43], v[44:45] op_sel:[0,1,0] op_sel_hi:[1,1,1]
	v_pk_fma_f32 v[46:47], v[82:83], v[42:43], v[46:47] op_sel:[0,1,0] op_sel_hi:[1,1,1]
	s_waitcnt lgkmcnt(2)
	v_fmac_f32_e32 v45, v85, v44
	v_pk_fma_f32 v[46:47], v[86:87], v[44:45], v[46:47] op_sel_hi:[1,0,1]
	s_waitcnt lgkmcnt(1)
	v_pk_fma_f32 v[46:47], v[90:91], v[44:45], v[46:47] op_sel:[0,1,0] op_sel_hi:[1,1,1]
	s_waitcnt lgkmcnt(0)
	v_fmac_f32_e32 v47, v95, v46
	v_cvt_pk_bf16_f32 v24, v32, v33
	v_cvt_pk_bf16_f32 v25, v34, v35
	v_cvt_pk_bf16_f32 v26, v36, v37
	v_cvt_pk_bf16_f32 v27, v38, v39
	v_cvt_pk_bf16_f32 v28, v40, v41
	v_cvt_pk_bf16_f32 v29, v42, v43
	v_cvt_pk_bf16_f32 v30, v44, v45
	v_cvt_pk_bf16_f32 v31, v46, v47
	ds_write_b128 v140, v[24:27]
	ds_write_b128 v140, v[28:31] offset:16
	s_setprio 0

.LBB0_422:
	s_or_b64 exec, exec, s[2:3]
	s_cmp_lt_u32 s36, 63
	s_cselect_b64 vcc, -1, 0
	s_cmp_gt_u32 s36, 62
	s_cbranch_scc1 .LBB0_424
	s_waitcnt vmcnt(10)
	v_lshlrev_b32_e32 v22, 16, v1
	v_and_b32_e32 v23, 0xffff0000, v1
	v_pk_mul_f32 v[24:25], v[102:103], v[22:23]
	s_waitcnt vmcnt(7)
	v_lshlrev_b32_e32 v26, 16, v3
	s_waitcnt vmcnt(6)
	v_pk_mul_f32 v[24:25], v[108:109], v[24:25] op_sel_hi:[0,1]
	v_and_b32_e32 v27, 0xffff0000, v3
	ds_write2_b64 v106, v[24:25], v[26:27] offset1:32
	v_lshlrev_b32_e32 v26, 16, v4
	v_and_b32_e32 v27, 0xffff0000, v4
	v_pk_add_f32 v[28:29], v[26:27], -1.0 op_sel_hi:[1,0]
	v_pk_mul_f32 v[24:25], v[26:27], v[24:25] neg_lo:[0,1] neg_hi:[0,1]
	v_pk_fma_f32 v[28:29], v[104:105], v[28:29], 1.0 op_sel_hi:[1,1,0]
	s_nop 0
	v_pk_mul_f32 v[22:23], v[28:29], v[22:23]
	ds_write2_b64 v106, v[22:23], v[24:25] offset0:64 offset1:96
	v_lshlrev_b32_e32 v22, 16, v0
	v_and_b32_e32 v23, 0xffff0000, v0
	v_lshlrev_b32_e32 v24, 16, v2
	v_and_b32_e32 v25, 0xffff0000, v2
	ds_write2_b64 v106, v[22:23], v[24:25] offset0:128 offset1:160
.LBB0_424:
.LBB0_426:
	s_add_i32 s24, s19, -16
	s_and_b64 s[2:3], s[12:13], exec
	s_waitcnt lgkmcnt(0)
	s_barrier
	s_cselect_b32 s2, s21, s24
	s_cmpk_lt_u32 s20, 0x7f
	ds_read_b64 v[236:237], v190
	v_lshl_add_u32 v194, s2, 6, v183
	s_cselect_b64 s[2:3], -1, 0
	v_lshl_add_u64 v[238:239], v[194:195], 1, s[78:79]
	s_and_b64 s[68:69], s[54:55], s[2:3]
	s_and_saveexec_b64 s[74:75], s[54:55]
	s_cbranch_execz .Lsx1_c
	s_cmp_gt_u32 s36, 61
	s_cbranch_scc1 .Lis1a
	s_add_i32 s24, s19, 0xffffffb0
	s_add_i32 s25, s21, 64
	s_and_b64 s[98:99], s[12:13], exec
	s_cselect_b32 s24, s25, s24
	v_lshl_add_u32 v194, s24, 6, v183
	v_lshlrev_b64 v[112:113], 1, v[194:195]
	v_lshl_add_u64 v[114:115], s[44:45], 0, v[112:113]
	global_load_dword v0, v[114:115], off
	v_lshl_add_u64 v[114:115], s[42:43], 0, v[112:113]
	global_load_dword v1, v[114:115], off
	v_lshl_add_u64 v[114:115], s[0:1], 0, v[112:113]
	global_load_dword v2, v[114:115], off
	v_lshl_add_u64 v[114:115], s[76:77], 0, v[112:113]
	global_load_dword v4, v[114:115], off
	v_lshl_add_u64 v[114:115], s[34:35], 0, v[112:113]
	global_load_dword v3, v[114:115], off
	v_add_u32_e32 v194, s24, v184
	v_lshl_add_u64 v[114:115], v[194:195], 2, s[40:41]
	global_load_dword v108, v[114:115], off
.Lis1a:
	s_waitcnt lgkmcnt(0)
	v_cvt_pk_bf16_f32 v240, v236, v237
	global_store_dword v[238:239], v240, off

.LBB0_432:
	s_or_b64 exec, exec, s[74:75]
	s_waitcnt lgkmcnt(0)
	s_barrier
	s_and_saveexec_b64 s[74:75], s[56:57]
	s_cbranch_execz .Lis1c
	s_cmp_gt_u32 s36, 61
	s_cbranch_scc1 .Lis1b
	s_add_i32 s24, s19, 0xffffffb0
	s_add_i32 s25, s21, 64
	s_and_b64 s[98:99], s[12:13], exec
	s_cselect_b32 s24, s25, s24
	v_lshl_add_u32 v194, s24, 6, v183
	v_lshlrev_b64 v[112:113], 1, v[194:195]
	v_lshl_add_u64 v[114:115], s[44:45], 0, v[112:113]
	global_load_dword v0, v[114:115], off
	v_lshl_add_u64 v[114:115], s[42:43], 0, v[112:113]
	global_load_dword v1, v[114:115], off
	v_lshl_add_u64 v[114:115], s[0:1], 0, v[112:113]
	global_load_dword v2, v[114:115], off
	v_lshl_add_u64 v[114:115], s[76:77], 0, v[112:113]
	global_load_dword v4, v[114:115], off
	v_lshl_add_u64 v[114:115], s[34:35], 0, v[112:113]
	global_load_dword v3, v[114:115], off
	v_add_u32_e32 v194, s24, v184
	v_lshl_add_u64 v[114:115], v[194:195], 2, s[40:41]
	global_load_dword v108, v[114:115], off
.Lis1b:
.Lis1c:
	s_or_b64 exec, exec, s[74:75]
	s_and_saveexec_b64 s[74:75], s[48:49]
	s_cbranch_execz .LBB0_434
	s_setprio 3
	v_mov_b32_e32 v23, 0x17900
	ds_read2st64_b32 v[32:33], v191 offset0:0 offset1:1
	ds_read_b128 v[48:51], v23 offset:0
	ds_read2st64_b32 v[34:35], v191 offset0:2 offset1:3
	ds_read2st64_b32 v[36:37], v191 offset0:4 offset1:5
	ds_read_b128 v[52:55], v23 offset:16
	ds_read2st64_b32 v[38:39], v191 offset0:6 offset1:7
	ds_read2st64_b32 v[40:41], v191 offset0:8 offset1:9
	ds_read_b128 v[56:59], v23 offset:32
	ds_read2st64_b32 v[42:43], v191 offset0:10 offset1:11
	ds_read2st64_b32 v[44:45], v191 offset0:12 offset1:13
	ds_read_b128 v[60:63], v23 offset:48
	ds_read2st64_b32 v[46:47], v191 offset0:14 offset1:15
	ds_read_b128 v[64:67], v23 offset:64
	ds_read_b128 v[68:71], v23 offset:80
	ds_read_b128 v[72:75], v23 offset:96
	s_waitcnt lgkmcnt(13)
	v_fmac_f32_e32 v33, v49, v32
	s_waitcnt lgkmcnt(12)
	v_pk_fma_f32 v[34:35], v[50:51], v[32:33], v[34:35] op_sel_hi:[1,0,1]
	ds_read_b128 v[76:79], v23 offset:112
	s_waitcnt lgkmcnt(11)
	v_pk_fma_f32 v[36:37], v[52:53], v[32:33], v[36:37] op_sel_hi:[1,0,1]
	ds_read_b128 v[80:83], v23 offset:128
	ds_read_b128 v[84:87], v23 offset:144
	s_waitcnt lgkmcnt(12)
	v_pk_fma_f32 v[38:39], v[54:55], v[32:33], v[38:39] op_sel_hi:[1,0,1]
	ds_read_b128 v[88:91], v23 offset:160
	s_waitcnt lgkmcnt(11)
	v_pk_fma_f32 v[40:41], v[56:57], v[32:33], v[40:41] op_sel_hi:[1,0,1]
	ds_read_b128 v[92:95], v23 offset:176
	ds_read_b128 v[112:115], v23 offset:208
	s_waitcnt lgkmcnt(12)
	v_pk_fma_f32 v[42:43], v[58:59], v[32:33], v[42:43] op_sel_hi:[1,0,1]
	ds_read_b128 v[116:119], v23 offset:224
	s_waitcnt lgkmcnt(11)
	v_pk_fma_f32 v[44:45], v[60:61], v[32:33], v[44:45] op_sel_hi:[1,0,1]
	ds_read_b128 v[120:123], v23 offset:240
	ds_read_b128 v[124:127], v23 offset:272
	s_waitcnt lgkmcnt(12)
	v_pk_fma_f32 v[46:47], v[62:63], v[32:33], v[46:47] op_sel_hi:[1,0,1]
	ds_read_b128 v[128:131], v23 offset:288
	s_waitcnt lgkmcnt(12)
	v_pk_fma_f32 v[34:35], v[66:67], v[32:33], v[34:35] op_sel:[0,1,0] op_sel_hi:[1,1,1]
	ds_read_b128 v[132:135], v23 offset:304
	s_waitcnt lgkmcnt(12)
	v_pk_fma_f32 v[36:37], v[68:69], v[32:33], v[36:37] op_sel:[0,1,0] op_sel_hi:[1,1,1]
	ds_read_b128 v[204:207], v23 offset:336
	v_pk_fma_f32 v[38:39], v[70:71], v[32:33], v[38:39] op_sel:[0,1,0] op_sel_hi:[1,1,1]
	s_waitcnt lgkmcnt(12)
	v_pk_fma_f32 v[40:41], v[72:73], v[32:33], v[40:41] op_sel:[0,1,0] op_sel_hi:[1,1,1]
	ds_read_b128 v[208:211], v23 offset:352
	v_pk_fma_f32 v[42:43], v[74:75], v[32:33], v[42:43] op_sel:[0,1,0] op_sel_hi:[1,1,1]
	s_waitcnt lgkmcnt(12)
	v_pk_fma_f32 v[44:45], v[76:77], v[32:33], v[44:45] op_sel:[0,1,0] op_sel_hi:[1,1,1]
	ds_read_b128 v[212:215], v23 offset:368
	v_pk_fma_f32 v[46:47], v[78:79], v[32:33], v[46:47] op_sel:[0,1,0] op_sel_hi:[1,1,1]
	s_waitcnt lgkmcnt(12)
	v_fmac_f32_e32 v35, v83, v34
	ds_read_b128 v[216:219], v23 offset:400
	s_waitcnt lgkmcnt(12)
	v_pk_fma_f32 v[36:37], v[84:85], v[34:35], v[36:37] op_sel_hi:[1,0,1]
	ds_read_b128 v[228:231], v23 offset:416
	v_pk_fma_f32 v[38:39], v[86:87], v[34:35], v[38:39] op_sel_hi:[1,0,1]
	s_waitcnt lgkmcnt(12)
	v_pk_fma_f32 v[40:41], v[88:89], v[34:35], v[40:41] op_sel_hi:[1,0,1]
	ds_read_b128 v[232:235], v23 offset:432
	v_pk_fma_f32 v[42:43], v[90:91], v[34:35], v[42:43] op_sel_hi:[1,0,1]
	s_waitcnt lgkmcnt(12)
	v_pk_fma_f32 v[44:45], v[92:93], v[34:35], v[44:45] op_sel_hi:[1,0,1]
	ds_read_b128 v[48:51], v23 offset:480
	v_pk_fma_f32 v[46:47], v[94:95], v[34:35], v[46:47] op_sel_hi:[1,0,1]
	s_waitcnt lgkmcnt(12)
	v_pk_fma_f32 v[36:37], v[112:113], v[34:35], v[36:37] op_sel:[0,1,0] op_sel_hi:[1,1,1]
	ds_read_b128 v[52:55], v23 offset:496
	v_pk_fma_f32 v[38:39], v[114:115], v[34:35], v[38:39] op_sel:[0,1,0] op_sel_hi:[1,1,1]
	s_waitcnt lgkmcnt(12)
	v_pk_fma_f32 v[40:41], v[116:117], v[34:35], v[40:41] op_sel:[0,1,0] op_sel_hi:[1,1,1]
	ds_read_b128 v[56:59], v23 offset:544
	v_pk_fma_f32 v[42:43], v[118:119], v[34:35], v[42:43] op_sel:[0,1,0] op_sel_hi:[1,1,1]
	s_waitcnt lgkmcnt(12)
	v_pk_fma_f32 v[44:45], v[120:121], v[34:35], v[44:45] op_sel:[0,1,0] op_sel_hi:[1,1,1]
	ds_read_b128 v[60:63], v23 offset:560
	v_pk_fma_f32 v[46:47], v[122:123], v[34:35], v[46:47] op_sel:[0,1,0] op_sel_hi:[1,1,1]
	s_waitcnt lgkmcnt(12)
	v_fmac_f32_e32 v37, v125, v36
	ds_read_b128 v[64:67], v23 offset:608
	v_pk_fma_f32 v[38:39], v[126:127], v[36:37], v[38:39] op_sel_hi:[1,0,1]
	s_waitcnt lgkmcnt(12)
	v_pk_fma_f32 v[40:41], v[128:129], v[36:37], v[40:41] op_sel_hi:[1,0,1]
	ds_read_b128 v[68:71], v23 offset:624
	v_pk_fma_f32 v[42:43], v[130:131], v[36:37], v[42:43] op_sel_hi:[1,0,1]
	s_waitcnt lgkmcnt(12)
	v_pk_fma_f32 v[44:45], v[132:133], v[36:37], v[44:45] op_sel_hi:[1,0,1]
	ds_read_b128 v[72:75], v23 offset:672
	v_pk_fma_f32 v[46:47], v[134:135], v[36:37], v[46:47] op_sel_hi:[1,0,1]
	s_waitcnt lgkmcnt(12)
	v_pk_fma_f32 v[38:39], v[206:207], v[36:37], v[38:39] op_sel:[0,1,0] op_sel_hi:[1,1,1]
	ds_read_b128 v[76:79], v23 offset:688
	s_waitcnt lgkmcnt(12)
	v_pk_fma_f32 v[40:41], v[208:209], v[36:37], v[40:41] op_sel:[0,1,0] op_sel_hi:[1,1,1]
	ds_read_b128 v[80:83], v23 offset:752
	v_pk_fma_f32 v[42:43], v[210:211], v[36:37], v[42:43] op_sel:[0,1,0] op_sel_hi:[1,1,1]
	s_waitcnt lgkmcnt(12)
	v_pk_fma_f32 v[44:45], v[212:213], v[36:37], v[44:45] op_sel:[0,1,0] op_sel_hi:[1,1,1]
	ds_read_b128 v[84:87], v23 offset:816
	v_pk_fma_f32 v[46:47], v[214:215], v[36:37], v[46:47] op_sel:[0,1,0] op_sel_hi:[1,1,1]
	s_waitcnt lgkmcnt(12)
	v_fmac_f32_e32 v39, v219, v38
	ds_read_b128 v[88:91], v23 offset:880
	s_waitcnt lgkmcnt(12)
	v_pk_fma_f32 v[40:41], v[228:229], v[38:39], v[40:41] op_sel_hi:[1,0,1]
	ds_read_b128 v[92:95], v23 offset:944
	v_pk_fma_f32 v[42:43], v[230:231], v[38:39], v[42:43] op_sel_hi:[1,0,1]
	s_waitcnt lgkmcnt(12)
	v_pk_fma_f32 v[44:45], v[232:233], v[38:39], v[44:45] op_sel_hi:[1,0,1]
	v_pk_fma_f32 v[46:47], v[234:235], v[38:39], v[46:47] op_sel_hi:[1,0,1]
	s_waitcnt lgkmcnt(11)
	v_pk_fma_f32 v[40:41], v[48:49], v[38:39], v[40:41] op_sel:[0,1,0] op_sel_hi:[1,1,1]
	v_pk_fma_f32 v[42:43], v[50:51], v[38:39], v[42:43] op_sel:[0,1,0] op_sel_hi:[1,1,1]
	s_waitcnt lgkmcnt(10)
	v_pk_fma_f32 v[44:45], v[52:53], v[38:39], v[44:45] op_sel:[0,1,0] op_sel_hi:[1,1,1]
	v_pk_fma_f32 v[46:47], v[54:55], v[38:39], v[46:47] op_sel:[0,1,0] op_sel_hi:[1,1,1]
	s_waitcnt lgkmcnt(9)
	v_fmac_f32_e32 v41, v57, v40
	v_pk_fma_f32 v[42:43], v[58:59], v[40:41], v[42:43] op_sel_hi:[1,0,1]
	s_waitcnt lgkmcnt(8)
	v_pk_fma_f32 v[44:45], v[60:61], v[40:41], v[44:45] op_sel_hi:[1,0,1]
	v_pk_fma_f32 v[46:47], v[62:63], v[40:41], v[46:47] op_sel_hi:[1,0,1]
	s_waitcnt lgkmcnt(7)
	v_pk_fma_f32 v[42:43], v[66:67], v[40:41], v[42:43] op_sel:[0,1,0] op_sel_hi:[1,1,1]
	s_waitcnt lgkmcnt(6)
	v_pk_fma_f32 v[44:45], v[68:69], v[40:41], v[44:45] op_sel:[0,1,0] op_sel_hi:[1,1,1]
	v_pk_fma_f32 v[46:47], v[70:71], v[40:41], v[46:47] op_sel:[0,1,0] op_sel_hi:[1,1,1]
	s_waitcnt lgkmcnt(5)
	v_fmac_f32_e32 v43, v75, v42
	s_waitcnt lgkmcnt(4)
	v_pk_fma_f32 v[44:45], v[76:77], v[42:43], v[44:45] op_sel_hi:[1,0,1]
	v_pk_fma_f32 v[46:47], v[78:79], v[42:43], v[46:47] op_sel_hi:[1,0,1]
	s_waitcnt lgkmcnt(3)
	v_pk_fma_f32 v[44:45], v[80:81], v[42:43], v[44:45] op_sel:[0,1,0] op_sel_hi:[1,1,1]
	v_pk_fma_f32 v[46:47], v[82:83], v[42:43], v[46:47] op_sel:[0,1,0] op_sel_hi:[1,1,1]
	s_waitcnt lgkmcnt(2)
	v_fmac_f32_e32 v45, v85, v44
	v_pk_fma_f32 v[46:47], v[86:87], v[44:45], v[46:47] op_sel_hi:[1,0,1]
	s_waitcnt lgkmcnt(1)
	v_pk_fma_f32 v[46:47], v[90:91], v[44:45], v[46:47] op_sel:[0,1,0] op_sel_hi:[1,1,1]
	s_waitcnt lgkmcnt(0)
	v_fmac_f32_e32 v47, v95, v46
	v_cvt_pk_bf16_f32 v24, v32, v33
	v_cvt_pk_bf16_f32 v25, v34, v35
	v_cvt_pk_bf16_f32 v26, v36, v37
	v_cvt_pk_bf16_f32 v27, v38, v39
	v_cvt_pk_bf16_f32 v28, v40, v41
	v_cvt_pk_bf16_f32 v29, v42, v43
	v_cvt_pk_bf16_f32 v30, v44, v45
	v_cvt_pk_bf16_f32 v31, v46, v47
	ds_write_b128 v140, v[24:27] offset:5120
	ds_write_b128 v140, v[28:31] offset:5136
	s_setprio 0

.LBB0_451:
	s_or_b64 exec, exec, s[2:3]
	s_andn2_b64 vcc, exec, vcc
	s_cbranch_vccnz .LBB0_453
	s_waitcnt vmcnt(10)
	v_lshlrev_b32_e32 v22, 16, v6
	v_and_b32_e32 v23, 0xffff0000, v6
	v_pk_mul_f32 v[24:25], v[102:103], v[22:23]
	s_waitcnt vmcnt(8)
	v_lshlrev_b32_e32 v26, 16, v8
	s_waitcnt vmcnt(6)
	v_pk_mul_f32 v[24:25], v[110:111], v[24:25] op_sel_hi:[0,1]
	v_and_b32_e32 v27, 0xffff0000, v8
	ds_write2_b64 v107, v[24:25], v[26:27] offset1:32
	v_lshlrev_b32_e32 v26, 16, v9
	v_and_b32_e32 v27, 0xffff0000, v9
	v_pk_add_f32 v[28:29], v[26:27], -1.0 op_sel_hi:[1,0]
	v_pk_mul_f32 v[24:25], v[26:27], v[24:25] neg_lo:[0,1] neg_hi:[0,1]
	v_pk_fma_f32 v[28:29], v[104:105], v[28:29], 1.0 op_sel_hi:[1,1,0]
	s_nop 0
	v_pk_mul_f32 v[22:23], v[28:29], v[22:23]
	ds_write2_b64 v107, v[22:23], v[24:25] offset0:64 offset1:96
	v_lshlrev_b32_e32 v22, 16, v5
	v_and_b32_e32 v23, 0xffff0000, v5
	v_lshlrev_b32_e32 v24, 16, v7
	v_and_b32_e32 v25, 0xffff0000, v7
	ds_write2_b64 v107, v[22:23], v[24:25] offset0:128 offset1:160
